# grid barrier: 16 designated workgroups start an L2 write-back at their own arrival (not waited for) so the final release write-back has less to do
# baseline (speedup 1.0000x reference)
.LBB0_272:
	s_or_b64 exec, exec, s[2:3]
	s_waitcnt vmcnt(0)
	s_waitcnt lgkmcnt(0)
	s_barrier
	s_and_b32 s98, s82, 15
	s_cmp_lg_u32 s98, 0
	s_cbranch_scc1 .Lefl_11
	v_readfirstlane_b32 s98, v246
	s_lshr_b32 s98, s98, 6
	s_cmp_lg_u32 s98, 1
	s_cbranch_scc1 .Lefl_11
	buffer_wbl2 sc1
.Lefl_11:
	s_and_saveexec_b64 s[2:3], s[4:5]
	s_cbranch_execz .LBB0_324
	v_readlane_b32 s8, v254, 29
	s_waitcnt vmcnt(0) expcnt(0) lgkmcnt(0)
	s_nop 0
	v_mov_b32_e32 v0, s8
	ds_read_b32 v2, v0
	v_readlane_b32 s8, v254, 30
	s_waitcnt lgkmcnt(0)
	v_cmp_ne_u32_e32 vcc, 0, v2
	v_mov_b32_e32 v0, s8
	ds_read_b32 v0, v0
	s_cbranch_vccnz .LBB0_288
	s_mov_b32 s14, 1
	s_branch .LBB0_276

.LBB0_334:
	s_or_b64 exec, exec, s[8:9]
	s_waitcnt lgkmcnt(0)
	s_xor_b64 s[2:3], s[6:7], -1
	s_waitcnt vmcnt(0)
	v_writelane_b32 v255, s2, 30
	s_barrier
	s_nop 0
	v_writelane_b32 v255, s3, 31
	s_and_b32 s98, s82, 15
	s_cmp_lg_u32 s98, 0
	s_cbranch_scc1 .Lefl_10
	v_readfirstlane_b32 s98, v246
	s_lshr_b32 s98, s98, 6
	s_cmp_lg_u32 s98, 1
	s_cbranch_scc1 .Lefl_10
	buffer_wbl2 sc1
.Lefl_10:
	s_and_saveexec_b64 s[2:3], s[4:5]
	s_cbranch_execz .LBB0_386
	v_readlane_b32 s6, v254, 29
	s_waitcnt vmcnt(0) expcnt(0) lgkmcnt(0)
	s_nop 0
	v_mov_b32_e32 v0, s6
	ds_read_b32 v2, v0
	v_readlane_b32 s6, v254, 30
	s_waitcnt lgkmcnt(0)
	v_cmp_ne_u32_e32 vcc, 0, v2
	v_mov_b32_e32 v0, s6
	ds_read_b32 v0, v0
	s_cbranch_vccnz .LBB0_350
	s_mov_b32 s12, 1
	s_branch .LBB0_338

.LBB0_523:
	s_waitcnt vmcnt(0)
	s_waitcnt vmcnt(0) lgkmcnt(0)
	s_barrier
	s_and_b32 s98, s82, 15
	s_cmp_lg_u32 s98, 0
	s_cbranch_scc1 .Lefl_9
	v_readfirstlane_b32 s98, v246
	s_lshr_b32 s98, s98, 6
	s_cmp_lg_u32 s98, 1
	s_cbranch_scc1 .Lefl_9
	buffer_wbl2 sc1

.LBB0_946:
	s_waitcnt vmcnt(0)
	s_waitcnt lgkmcnt(0)
	s_barrier
	s_and_b32 s98, s82, 15
	s_cmp_lg_u32 s98, 0
	s_cbranch_scc1 .Lefl_7
	v_readfirstlane_b32 s98, v246
	s_lshr_b32 s98, s98, 6
	s_cmp_lg_u32 s98, 1
	s_cbranch_scc1 .Lefl_7
	buffer_wbl2 sc1

.LBB0_1353:
	s_mov_b32 s77, 0x800000
	s_or_b64 exec, exec, s[2:3]
	s_waitcnt vmcnt(0)
	s_waitcnt lgkmcnt(0)
	s_barrier
	s_and_b32 s98, s82, 15
	s_cmp_lg_u32 s98, 0
	s_cbranch_scc1 .Lefl_5
	v_readfirstlane_b32 s98, v246
	s_lshr_b32 s98, s98, 6
	s_cmp_lg_u32 s98, 1
	s_cbranch_scc1 .Lefl_5
	buffer_wbl2 sc1

.Lmg_gsync_do:
	s_and_b32 s98, s82, 15
	s_cmp_lg_u32 s98, 0
	s_cbranch_scc1 .Lefl_4
	v_readfirstlane_b32 s98, v246
	s_lshr_b32 s98, s98, 6
	s_cmp_lg_u32 s98, 1
	s_cbranch_scc1 .Lefl_4
	buffer_wbl2 sc1

.LBB0_1624:
	s_or_b64 exec, exec, s[8:9]
	s_waitcnt vmcnt(0)
	s_waitcnt lgkmcnt(0)
	s_barrier
	s_and_b32 s98, s82, 15
	s_cmp_lg_u32 s98, 0
	s_cbranch_scc1 .Lefl_2
	v_readfirstlane_b32 s98, v246
	s_lshr_b32 s98, s98, 6
	s_cmp_lg_u32 s98, 1
	s_cbranch_scc1 .Lefl_2
	buffer_wbl2 sc1
.Lefl_2:
	s_and_saveexec_b64 s[8:9], s[4:5]
	s_cbranch_execz .LBB0_1676
	v_readlane_b32 s10, v254, 29
	s_waitcnt vmcnt(0) expcnt(0) lgkmcnt(0)
	s_nop 0
	v_mov_b32_e32 v0, s10
	ds_read_b32 v2, v0
	v_readlane_b32 s10, v254, 30
	s_waitcnt lgkmcnt(0)
	v_cmp_ne_u32_e32 vcc, 0, v2
	v_mov_b32_e32 v0, s10
	ds_read_b32 v0, v0
	s_cbranch_vccnz .LBB0_1640
	s_mov_b32 s16, 1
	s_branch .LBB0_1628

.Lefl_1:
	s_and_saveexec_b64 s[10:11], s[4:5]
	s_cbranch_execz .LBB0_1744
	v_readlane_b32 s12, v254, 29
	s_waitcnt vmcnt(0) expcnt(0) lgkmcnt(0)
	s_nop 0
	v_mov_b32_e32 v0, s12
	ds_read_b32 v2, v0
	v_readlane_b32 s12, v254, 30
	s_waitcnt lgkmcnt(0)
	v_cmp_ne_u32_e32 vcc, 0, v2
	v_mov_b32_e32 v0, s12
	ds_read_b32 v0, v0
	s_cbranch_vccnz .LBB0_1708
	s_mov_b32 s18, 1
	s_branch .LBB0_1696

.Lnot_last_layer:
	s_barrier
	s_and_b32 s98, s82, 15
	s_cmp_lg_u32 s98, 0
	s_cbranch_scc1 .Lefl_0
	v_readfirstlane_b32 s98, v246
	s_lshr_b32 s98, s98, 6
	s_cmp_lg_u32 s98, 1
	s_cbranch_scc1 .Lefl_0
	buffer_wbl2 sc1
.Lefl_0:
	s_and_saveexec_b64 s[2:3], s[4:5]
	s_cbranch_execnz .LBB0_1795
	s_getpc_b64 s[98:99]
